# P4 CU-aware placement: workgroups publish their CU id (HW_ID), the two workgroups sharing a CU take P4 tiles that share neither operand block (index p / p^36 by CU-key rank; validated bijection, fallb
# speedup vs baseline: 1.0028x; 1.0028x over previous
.LBB0_647:
	s_or_b64 exec, exec, s[0:1]
	s_getreg_b32 s100, hwreg(HW_REG_HW_ID)
	s_bfe_u32 s100, s100, 0x80008
	v_readlane_b32 s98, v252, 10
	v_readlane_b32 s99, v252, 11
	v_readlane_b32 s101, v254, 38
	s_lshl_b32 s101, s101, 8
	s_add_u32 s101, s101, 0x3604
	s_add_u32 s98, s98, s101
	s_addc_u32 s99, s99, 0
	v_mov_b32_e32 v220, s100
	v_mov_b32_e32 v221, s72
	v_cmp_eq_u32_e32 vcc, 0, v199
	s_and_saveexec_b64 s[100:101], vcc
	global_store_byte v221, v220, s[98:99]
	s_mov_b64 exec, s[100:101]
	v_readlane_b32 s0, v254, 26
	v_readlane_b32 s1, v254, 27
	v_mov_b32_e32 v167, v199
	s_andn2_b64 vcc, exec, s[0:1]
	v_cndmask_b32_e64 v0, 0, 1, s[0:1]
	v_cmp_ne_u32_e64 s[36:37], 1, v0
	s_mov_b32 s50, s72
	s_waitcnt lgkmcnt(0)
	s_barrier
	s_cbranch_vccz .LBB0_652

.LBB0_843:
	s_or_b64 exec, exec, s[0:1]
	v_mov_b32_e32 v0, v199
	s_and_b64 vcc, exec, s[36:37]
	s_waitcnt lgkmcnt(0)
	s_barrier
	s_cbranch_vccnz .LBB0_865
	v_ashrrev_i32_e32 v165, 6, v0
	v_readlane_b32 s98, v252, 10
	v_readlane_b32 s99, v252, 11
	v_readlane_b32 s100, v254, 38
	s_lshl_b32 s100, s100, 8
	s_add_u32 s100, s100, 0x3604
	s_add_u32 s98, s98, s100
	s_addc_u32 s99, s99, 0
	v_and_b32_e32 v222, 63, v199
	global_load_ubyte v221, v222, s[98:99]
	s_waitcnt vmcnt(0)
	v_mov_b32_e32 v223, 0
	s_mov_b32 s100, 0
.Lcu_loop:
	s_nop 1
	v_readlane_b32 s101, v221, s100
	s_nop 3
	v_cmp_eq_u32_e32 vcc, s101, v221
	s_nop 1
	v_addc_co_u32_e32 v223, vcc, 0, v223, vcc
	s_add_u32 s100, s100, 1
	s_cmp_lt_u32 s100, 64
	s_cbranch_scc1 .Lcu_loop
	v_readlane_b32 s98, v221, s72
	v_cmp_ne_u32_e32 vcc, 2, v223
	s_nop 3
	s_cmp_eq_u64 vcc, 0
	s_cselect_b32 s99, 1, 0
	s_cmp_eq_u32 s73, 64
	s_cselect_b32 s99, s99, 0
	v_cmp_eq_u32_e32 vcc, s98, v221
	v_cmp_gt_u32_e64 s[100:101], s72, v222
	s_nop 3
	s_and_b64 s[100:101], s[100:101], vcc
	s_bcnt1_i32_b64 s101, s[100:101]
	v_cmp_gt_u32_e32 vcc, s98, v221
	s_nop 3
	s_bcnt1_i32_b64 s100, vcc
	s_lshr_b32 s100, s100, 1
	s_mul_i32 s101, s101, 36
	s_xor_b32 s100, s100, s101
	s_cmp_eq_u32 s99, 1
	s_cselect_b32 s100, s100, s72
	s_lshl_b32 s101, s72, 8
	s_or_b32 s100, s100, s101
	s_or_b32 s100, s100, 0xc0de0000
	v_mov_b32_e32 v220, s100
	v_mov_b32_e32 v221, 0x1200c
	ds_write_b32 v221, v220
	s_waitcnt lgkmcnt(0)
	s_mov_b32 s50, s72
	s_branch .LBB0_847

.LBB0_913:
	s_or_b64 exec, exec, s[0:1]
	v_readlane_b32 s0, v254, 45
	v_readlane_b32 s1, v254, 46
	v_mov_b32_e32 v0, v199
	s_andn2_b64 vcc, exec, s[0:1]
	s_waitcnt lgkmcnt(0)
	s_barrier
	s_cbranch_vccnz .LBB0_943
	v_readlane_b32 s12, v255, 14
	v_readlane_b32 s40, v252, 34
	s_mul_i32 s0, s12, 0x1c0000
	v_readlane_b32 s42, v252, 36
	v_readlane_b32 s43, v252, 37
	s_add_u32 s56, s42, s0
	s_addc_u32 s57, s43, 0
	s_mul_i32 s0, s12, 0x600000
	v_readlane_b32 s41, v252, 35
	s_add_u32 s0, s40, s0
	s_addc_u32 s1, s41, 0
	s_mov_b32 s58, 0
	v_mov_b32_e32 v220, 0x1200c
	ds_read_b32 v220, v220
	s_waitcnt lgkmcnt(0)
	v_readfirstlane_b32 s98, v220
	s_lshr_b32 s99, s98, 16
	s_cmp_eq_u32 s99, 0xc0de
	s_cbranch_scc0 .Lp4_noremap
	s_and_b32 s72, s98, 0xff

.LBB0_942:
	v_mov_b32_e32 v220, 0x1200c
	ds_read_b32 v220, v220
	s_waitcnt lgkmcnt(0)
	v_readfirstlane_b32 s98, v220
	s_lshr_b32 s99, s98, 16
	s_cmp_eq_u32 s99, 0xc0de
	s_cbranch_scc0 .Lp4_norest
	s_bfe_u32 s72, s98, 0x80008
